# P2 summary units: gate pre-activation loads software-pipelined one unit ahead (loop-slack prefetch into spare VGPRs, counted vmcnt(16) at the consumer)
# baseline (speedup 1.0000x reference)
; __global__ void __launch_bounds__(512, 2) mega(Args args) {
;     ...
;         constexpr int NSU = NCHUNK * 4, NAU = (NCHUNK / 2) * 4;
;         u32x4 v8r[4], k8r[4];
;         if ((int)blockIdx.x < NSU) summary_prefetch(c, (int)blockIdx.x >> 2, (int)blockIdx.x & 3, tid, v8r, k8r);
;         for (int it0 = blockIdx.x; it0 < (((DUP_MASK >> 2) & 1) ? 2 : 1) * (NSU + NAU); it0 += G) { const int it = it0 >= NSU + NAU ? it0 - (NSU + NAU) : it0;
.LBB0_203:
	v_writelane_b32 v252, s8, 36
	s_mov_b32 s80, s84
	s_mov_b64 s[68:69], s[72:73]
	v_writelane_b32 v252, s9, 37
	s_mov_b32 s35, 0
	v_readlane_b32 s8, v252, 0
	s_lshr_b32 s83, s8, 8
	s_and_b32 s84, s8, 0xc0
	s_cmpk_gt_u32 s84, 0x7f
	s_cselect_b64 s[20:21], -1, 0
	s_or_b32 s85, s84, 0x100
	s_or_b32 s86, s84, 0x110
	s_or_b32 s87, s84, 32
	s_or_b32 s88, s84, 0x120
	s_or_b32 s89, s84, 0x130
	s_cmpk_gt_u32 s8, 0x7f
	s_cselect_b64 s[30:31], -1, 0
	s_cmp_lt_u32 s8, 64
	v_readlane_b32 s3, v252, 2
	s_cselect_b64 s[0:1], -1, 0
	s_lshl_b32 s2, s3, 9
	s_add_i32 s90, s2, 0
	s_add_i32 s90, s90, 0x19800
	s_bfe_u32 s93, s8, 0x10006
	s_cmp_eq_u32 s93, 0
	s_mov_b32 s2, 0x8800
	s_cselect_b32 s2, s2, 0x11000
	s_add_i32 s91, s2, 0
	s_lshl_b32 s2, s3, 4
	s_and_b32 s92, s2, 0x3fffffe0
	v_readlane_b32 s4, v252, 22
	v_readlane_b32 s5, v252, 23
	s_add_u32 s40, s4, 0x1d000000
	s_addc_u32 s41, s5, 0
	s_add_u32 s42, s4, 0x1f800000
	s_addc_u32 s43, s5, 0
	s_add_u32 s44, s4, 0x18000000
	s_addc_u32 s45, s5, 0
	s_add_u32 s46, s81, s2
	s_addc_u32 s47, s77, 0
	s_add_u32 s71, s4, 0x2e00000
	s_addc_u32 s72, s5, 0
	s_add_u32 s52, s4, 0x9000000
	s_addc_u32 s53, s5, 0
	s_add_u32 s54, s4, 0xe000000
	s_addc_u32 s55, s5, 0
	s_bfe_u32 s2, s8, 0x20006
	s_mul_i32 s96, s2, 0x2400
	v_mbcnt_lo_u32_b32 v8, -1, 0
	s_mulk_i32 s93, 0x280
	s_mov_b32 s70, s77
	s_addk_i32 s96, 0x2400
	s_lshl_b32 s97, s2, 7
	s_mov_b32 s66, 0x2aaaaaab
	s_mov_b32 s67, 0xffffffa
	s_movk_i32 s94, 0x80
	s_mov_b32 s33, s95
	s_movk_i32 s95, 0x180
	v_mov_b32_e32 v9, 0
	s_movk_i32 s79, 0x90
	s_add_i32 s78, 0, 0x12000
	s_movk_i32 s77, 0x410
	s_mov_b32 s73, 0x3fb8aa3b
	s_mov_b32 s18, 0xff800000
	v_mov_b32_e32 v153, 0x3ecc95a3
	s_movk_i32 s19, 0x88
	v_mbcnt_hi_u32_b32 v154, -1, v8
	v_mov_b32_e32 v155, 0xff800000
	v_mov_b32_e32 v156, 0x7f800000
	v_mov_b32_e32 v148, 0x3f317218
	v_bfrev_b32_e32 v157, 0.5
	v_mov_b32_e32 v158, 0x3f80
	v_readlane_b32 s6, v252, 24
	v_readlane_b32 s7, v252, 25
	v_lshlrev_b32_e32 v196, 1, v212
	v_sub_u32_e32 v197, 0x7f, v196
	v_cndmask_b32_e64 v197, v197, v196, s[0:1]
	v_or_b32_e32 v198, 1, v196
	v_sub_u32_e32 v199, 0x7f, v198
	v_cndmask_b32_e64 v198, v199, v198, s[0:1]
	s_lshr_b32 s2, s33, 2
	s_lshl_b32 s2, s2, 7
	s_and_b32 s3, s33, 3
	s_lshl_b32 s3, s3, 2
	v_add_u32_e32 v197, s2, v197
	v_add_u32_e32 v198, s2, v198
	v_lshlrev_b32_e32 v197, 6, v197
	v_lshlrev_b32_e32 v198, 6, v198
	v_add_u32_e32 v197, s3, v197
	v_add_u32_e32 v198, s3, v198
	global_load_dword v192, v197, s[46:47]
	global_load_dword v193, v197, s[46:47] offset:32
	global_load_dword v194, v198, s[46:47]
	global_load_dword v195, v198, s[46:47] offset:32
	s_waitcnt vmcnt(0)
	s_branch .LBB0_206

; DI float logsigmoid_(float x) { return x >= 0.f ? -log1pf(expf(-x)) : x - log1pf(expf(x)); }
; DI ChunkVec chunk_vectors_from(const ChunkGates& q, int lane) {
;     ChunkVec r; r.s0 = q.s0; r.s1 = q.s1;
;     const float i0 = q.i0, f0 = q.f0, i1 = q.i1, f1 = q.f1;
;     const float lf0 = logsigmoid_(f0), lf1 = logsigmoid_(f1);
.LBB0_288:
	s_ashr_i32 s13, s33, 2
	s_andn2_b64 vcc, exec, s[2:3]
	v_lshlrev_b32_e32 v38, 1, v8
	s_cbranch_vccnz .LBB0_300
	v_or_b32_e32 v10, 1, v38
	v_sub_u32_e32 v11, 0x7f, v38
	s_lshl_b32 s2, s13, 7
	v_cndmask_b32_e64 v11, v11, v38, s[0:1]
	v_sub_u32_e32 v36, 0x7f, v10
	v_cndmask_b32_e64 v36, v36, v10, s[0:1]
	v_add_u32_e32 v40, s2, v11
	v_ashrrev_i32_e32 v41, 31, v40
	v_add_u32_e32 v42, s2, v36
	v_lshlrev_b64 v[40:41], 6, v[40:41]
	v_ashrrev_i32_e32 v43, 31, v42
	v_lshl_add_u64 v[40:41], s[46:47], 0, v[40:41]
	s_lshl_b32 s34, s12, 2
	v_lshlrev_b64 v[42:43], 6, v[42:43]
	v_lshl_add_u64 v[40:41], v[40:41], 0, s[34:35]
	v_lshl_add_u64 v[42:43], s[46:47], 0, v[42:43]
	v_lshl_add_u64 v[44:45], v[42:43], 0, s[34:35]
	s_waitcnt vmcnt(16)
	v_mov_b32_e32 v10, v192
	v_mov_b32_e32 v42, v193
	v_mov_b32_e32 v37, v194
	v_mov_b32_e32 v40, v195
	v_cmp_le_f32_e32 vcc, 0, v42
	s_and_saveexec_b64 s[2:3], vcc
	s_xor_b64 s[2:3], exec, s[2:3]
	s_cbranch_execz .LBB0_291
	v_mul_f32_e32 v41, 0xbfb8aa3b, v42
	v_rndne_f32_e32 v43, v41
	s_mov_b32 s4, 0xbfb8aa3b
	v_sub_f32_e32 v44, v41, v43
	v_fma_f32 v41, v42, s4, -v41
	v_fmac_f32_e32 v41, 0xb2a5705f, v42
	v_add_f32_e32 v41, v44, v41
	v_cvt_i32_f32_e32 v43, v43
	v_exp_f32_e32 v41, v41
	s_mov_b32 s4, 0x42ce8ed0
	v_cmp_nlt_f32_e32 vcc, s4, v42
	s_mov_b32 s4, 0xc2b17218
	v_ldexp_f32 v41, v41, v43
	v_cndmask_b32_e32 v41, 0, v41, vcc
	v_cmp_ngt_f32_e32 vcc, s4, v42
	s_mov_b32 s4, 0x3f2aaaab
	s_nop 0
	v_cndmask_b32_e32 v41, v156, v41, vcc
	v_add_f32_e32 v44, 1.0, v41
	v_add_f32_e32 v42, -1.0, v44
	v_sub_f32_e32 v43, v42, v44
	v_add_f32_e32 v43, 1.0, v43
	v_sub_f32_e32 v42, v41, v42
	v_add_f32_e32 v45, v42, v43
	v_frexp_mant_f32_e32 v46, v44
	v_cvt_f64_f32_e32 v[42:43], v44
	v_frexp_exp_i32_f64_e32 v42, v[42:43]
	v_cmp_gt_f32_e32 vcc, s4, v46
	s_mov_b32 s4, 0x3f317218
	s_nop 0
	v_subbrev_co_u32_e32 v50, vcc, 0, v42, vcc
	v_sub_u32_e32 v42, 0, v50
	v_ldexp_f32 v43, v44, v42
	v_add_f32_e32 v44, -1.0, v43
	v_add_f32_e32 v46, 1.0, v43
	v_ldexp_f32 v42, v45, v42
	v_add_f32_e32 v45, 1.0, v44
	v_add_f32_e32 v47, -1.0, v46
	v_sub_f32_e32 v45, v43, v45
	v_sub_f32_e32 v43, v43, v47
	v_add_f32_e32 v45, v42, v45
	v_add_f32_e32 v42, v42, v43
	v_add_f32_e32 v51, v46, v42
	v_rcp_f32_e32 v53, v51
	v_sub_f32_e32 v43, v46, v51
	v_add_f32_e32 v52, v42, v43
	v_add_f32_e32 v43, v44, v45
	v_mul_f32_e32 v55, v43, v53
	v_sub_f32_e32 v42, v44, v43
	v_mul_f32_e32 v44, v51, v55
	v_fma_f32 v46, v55, v51, -v44
	v_fmac_f32_e32 v46, v55, v52
	v_add_f32_e32 v54, v45, v42
	v_add_f32_e32 v42, v44, v46
	v_sub_f32_e32 v45, v43, v42
	v_pk_add_f32 v[48:49], v[42:43], v[44:45] neg_lo:[0,1] neg_hi:[0,1]
	v_mov_b32_e32 v47, v42
	v_pk_add_f32 v[42:43], v[48:49], v[46:47] neg_lo:[0,1] neg_hi:[0,1]
	s_nop 0
	v_add_f32_e32 v43, v54, v43
	v_add_f32_e32 v42, v42, v43
	v_add_f32_e32 v43, v45, v42
	v_mul_f32_e32 v54, v53, v43
	v_mul_f32_e32 v44, v51, v54
	v_fma_f32 v46, v54, v51, -v44
	v_fmac_f32_e32 v46, v54, v52
	v_sub_f32_e32 v45, v45, v43
	v_add_f32_e32 v51, v42, v45
	v_add_f32_e32 v42, v44, v46
	v_sub_f32_e32 v45, v43, v42
	v_pk_add_f32 v[48:49], v[42:43], v[44:45] neg_lo:[0,1] neg_hi:[0,1]
	v_mov_b32_e32 v47, v42
	v_pk_add_f32 v[42:43], v[48:49], v[46:47] neg_lo:[0,1] neg_hi:[0,1]
	s_nop 0
	v_add_f32_e32 v43, v51, v43
	v_add_f32_e32 v42, v42, v43
	v_add_f32_e32 v43, v55, v54
	v_add_f32_e32 v42, v45, v42
	v_sub_f32_e32 v44, v43, v55
	v_mul_f32_e32 v42, v53, v42
	v_sub_f32_e32 v44, v54, v44
	v_add_f32_e32 v44, v44, v42
	v_add_f32_e32 v46, v43, v44
	v_mul_f32_e32 v47, v46, v46
	v_fmamk_f32 v42, v47, 0x3e9b6dac, v153
	v_fmaak_f32 v149, v47, v42, 0x3f2aaada
	v_cvt_f32_i32_e32 v42, v50
	v_sub_f32_e32 v43, v46, v43
	v_sub_f32_e32 v43, v44, v43
	v_ldexp_f32 v48, v43, 1
	v_mul_f32_e32 v43, v46, v47
	v_ldexp_f32 v45, v46, 1
	v_pk_mul_f32 v[46:47], v[42:43], v[148:149]
	s_nop 0
	v_fma_f32 v44, v42, s4, -v46
	v_fmac_f32_e32 v44, 0xb102e308, v42
	v_pk_add_f32 v[42:43], v[46:47], v[44:45]
	s_mov_b32 s4, 0x7f800000
	v_sub_f32_e32 v45, v43, v45
	v_sub_f32_e32 v45, v47, v45
	v_add_f32_e32 v49, v48, v45
	v_mov_b32_e32 v48, v46
	v_pk_add_f32 v[46:47], v[42:43], v[46:47] neg_lo:[0,1] neg_hi:[0,1]
	v_pk_add_f32 v[50:51], v[42:43], v[48:49]
	v_mov_b32_e32 v45, v42
	v_mov_b32_e32 v47, v51
	v_pk_add_f32 v[52:53], v[44:45], v[46:47] neg_lo:[0,1] neg_hi:[0,1]
	v_pk_add_f32 v[44:45], v[44:45], v[46:47]
	v_mov_b32_e32 v48, v49
	v_pk_add_f32 v[46:47], v[44:45], v[42:43] op_sel:[1,0] op_sel_hi:[0,1] neg_lo:[0,1] neg_hi:[0,1]
	v_pk_add_f32 v[54:55], v[50:51], v[46:47] op_sel_hi:[1,0] neg_lo:[0,1] neg_hi:[0,1]
	v_mov_b32_e32 v50, v51
	v_mov_b32_e32 v51, v45
	v_pk_mov_b32 v[46:47], v[42:43], v[46:47] op_sel:[1,0]
	v_mov_b32_e32 v49, v42
	v_pk_add_f32 v[46:47], v[50:51], v[46:47] neg_lo:[0,1] neg_hi:[0,1]
	v_mov_b32_e32 v54, v52
	v_pk_add_f32 v[42:43], v[48:49], v[46:47] neg_lo:[0,1] neg_hi:[0,1]
	v_mov_b32_e32 v53, v45
	v_pk_add_f32 v[46:47], v[54:55], v[42:43]
	v_cmp_neq_f32_e32 vcc, s4, v41
	v_pk_add_f32 v[48:49], v[46:47], v[46:47] op_sel:[0,1] op_sel_hi:[1,0]
	s_mov_b32 s4, 0x33800000
	v_pk_add_f32 v[44:45], v[44:45], v[48:49] op_sel:[1,0] op_sel_hi:[0,1]
	v_mov_b32_e32 v47, v44
	v_pk_add_f32 v[50:51], v[46:47], v[52:53] neg_lo:[0,1] neg_hi:[0,1]
	v_mov_b32_e32 v43, v48
	v_sub_f32_e32 v45, v46, v50
	v_pk_add_f32 v[42:43], v[42:43], v[50:51] neg_lo:[0,1] neg_hi:[0,1]
	v_sub_f32_e32 v45, v52, v45
	v_add_f32_e32 v42, v42, v45
	v_add_f32_e32 v42, v42, v43
	v_add_f32_e32 v42, v44, v42
	v_cndmask_b32_e32 v42, v156, v42, vcc
	v_cmp_gt_f32_e32 vcc, s4, v41
	s_nop 1
	v_cndmask_b32_e32 v41, v42, v41, vcc
	v_xor_b32_e32 v41, 0x80000000, v41

; DI unsigned pk2(float lo, float hi) { const f32n2 v = {lo, hi}; return __builtin_bit_cast(unsigned, __builtin_convertvector(v, bf16n2)); }
; DI float bflo(unsigned w) { return __uint_as_float(w << 16); }
; DI float bfhi(unsigned w) { return __uint_as_float(w & 0xffff0000u); }
; DI void summary_unit(LAS unsigned char* lds, const Ctx& c, int chunk, int head, int nchunk, int nhead, u32x4 (&v8r)[4], u32x4 (&k8r)[4], int tid, int lane, int wid) {
;     ...
;     __syncthreads();
; #pragma unroll
;     for (int i = 0; i < 4; ++i) { const int idx = tid + 512 * i, s = idx & 127, ch = idx >> 7;
;         const u32x4 v8 = v8r[i], k8 = k8r[i]; const float wf = vW[s], wb = vW[128 + s];
; #pragma unroll
;         for (int e = 0; e < 8; ++e) { const unsigned vw = v8[e >> 1], kw = k8[e >> 1]; const float kf = (e & 1) ? bfhi(kw) : bflo(kw);
;             LVT[(8 * ch + e) * 136 + s] = (bf16_t)((e & 1) ? (vw >> 16) : (vw & 0xffffu));
;             const unsigned fb = pk2(wf * kf, wb * kf); LKF[(8 * ch + e) * 136 + s] = (bf16_t)(fb & 0xffffu); LKB[(8 * ch + e) * 136 + s] = (bf16_t)(fb >> 16); } }
.LBB0_300:
	v_and_b32_e32 v11, 0x7f, v39
	s_waitcnt lgkmcnt(0)
	v_lshl_add_u32 v10, v11, 2, 0
	v_add_u32_e32 v10, 0x19800, v10
	s_waitcnt vmcnt(0)
	s_barrier
	ds_read2st64_b32 v[36:37], v10 offset1:2
	v_ashrrev_i32_e32 v42, 4, v39
	s_add_i32 s6, s33, s76
	v_and_b32_e32 v10, -8, v42
	s_cmpk_lt_i32 s6, 0xa00
	v_lshlrev_b32_e32 v40, 16, v32
	v_mul_lo_u32 v41, v10, s19
	s_cselect_b32 s2, s6, s33
	v_add_lshl_u32 v43, v41, v11, 1
	s_waitcnt lgkmcnt(0)
	v_pk_mul_f32 v[40:41], v[36:37], v[40:41] op_sel_hi:[1,0]
	s_add_i32 s3, 0, 0x11000
	v_add_u32_e32 v44, 0, v43
	v_cvt_pk_bf16_f32 v40, v40, v41
	v_add_u32_e32 v43, s3, v43
	v_and_b32_e32 v32, 0xffff0000, v32
	ds_write_b16 v44, v40 offset:34816
	ds_write_b16_d16_hi v43, v40
	v_pk_mul_f32 v[40:41], v[36:37], v[32:33] op_sel_hi:[1,0]
	ds_write_b16 v44, v28
	ds_write_b16_d16_hi v44, v28 offset:272
	v_cvt_pk_bf16_f32 v28, v40, v41
	ds_write_b16 v44, v28 offset:35088
	ds_write_b16_d16_hi v43, v28 offset:272
	v_lshlrev_b32_e32 v28, 16, v33
	v_pk_mul_f32 v[40:41], v[36:37], v[28:29] op_sel_hi:[1,0]
	ds_write_b16 v44, v29 offset:544
	v_cvt_pk_bf16_f32 v28, v40, v41
	ds_write_b16 v44, v28 offset:35360
	ds_write_b16_d16_hi v43, v28 offset:544
	v_and_b32_e32 v28, 0xffff0000, v33
	ds_write_b16_d16_hi v44, v29 offset:816
	v_pk_mul_f32 v[28:29], v[36:37], v[28:29] op_sel_hi:[1,0]
	v_and_b32_e32 v68, 15, v8
	v_cvt_pk_bf16_f32 v28, v28, v29
	ds_write_b16 v44, v28 offset:35632
	ds_write_b16_d16_hi v43, v28 offset:816
	v_lshlrev_b32_e32 v28, 16, v34
	v_pk_mul_f32 v[28:29], v[36:37], v[28:29] op_sel_hi:[1,0]
	ds_write_b16 v44, v30 offset:1088
	v_cvt_pk_bf16_f32 v28, v28, v29
	ds_write_b16 v44, v28 offset:35904
	ds_write_b16_d16_hi v43, v28 offset:1088
	v_and_b32_e32 v28, 0xffff0000, v34
	v_pk_mul_f32 v[28:29], v[36:37], v[28:29] op_sel_hi:[1,0]
	ds_write_b16_d16_hi v44, v30 offset:1360
	v_cvt_pk_bf16_f32 v28, v28, v29
	ds_write_b16 v44, v28 offset:36176
	ds_write_b16_d16_hi v43, v28 offset:1360
	v_lshlrev_b32_e32 v28, 16, v35
	v_pk_mul_f32 v[28:29], v[36:37], v[28:29] op_sel_hi:[1,0]
	ds_write_b16 v44, v31 offset:1632
	v_cvt_pk_bf16_f32 v28, v28, v29
	v_or_b32_e32 v29, 7, v42
	ds_write_b16 v44, v28 offset:36448
	ds_write_b16_d16_hi v43, v28 offset:1632
	v_and_b32_e32 v28, 0xffff0000, v35
	v_mul_lo_u32 v29, v29, s19
	v_add_lshl_u32 v30, v29, v11, 1
	v_pk_mul_f32 v[28:29], v[36:37], v[28:29] op_sel_hi:[1,0]
	v_add_u32_e32 v32, 0, v30
	v_cvt_pk_bf16_f32 v28, v28, v29
	v_add_u32_e32 v29, s3, v30
	ds_write_b16 v32, v28 offset:34816
	ds_write_b16_d16_hi v29, v28
	v_add_u32_e32 v28, 0x200, v39
	v_ashrrev_i32_e32 v30, 4, v28
	v_and_b32_e32 v40, -8, v30
	v_lshlrev_b32_e32 v28, 16, v24
	v_mul_lo_u32 v29, v40, s19
	ds_write_b16_d16_hi v32, v31
	v_add_lshl_u32 v31, v29, v11, 1
	v_pk_mul_f32 v[28:29], v[36:37], v[28:29] op_sel_hi:[1,0]
	v_add_u32_e32 v32, 0, v31
	v_cvt_pk_bf16_f32 v28, v28, v29
	v_add_u32_e32 v31, s3, v31
	v_and_b32_e32 v24, 0xffff0000, v24
	ds_write_b16 v32, v28 offset:34816
	ds_write_b16_d16_hi v31, v28
	v_pk_mul_f32 v[28:29], v[36:37], v[24:25] op_sel_hi:[1,0]
	ds_write_b16 v32, v20
	ds_write_b16_d16_hi v32, v20 offset:272
	v_cvt_pk_bf16_f32 v20, v28, v29
	ds_write_b16 v32, v20 offset:35088
	ds_write_b16_d16_hi v31, v20 offset:272
	v_lshlrev_b32_e32 v20, 16, v25
	v_pk_mul_f32 v[28:29], v[36:37], v[20:21] op_sel_hi:[1,0]
	ds_write_b16 v32, v21 offset:544
	v_cvt_pk_bf16_f32 v20, v28, v29
	ds_write_b16 v32, v20 offset:35360
	ds_write_b16_d16_hi v31, v20 offset:544
	v_and_b32_e32 v20, 0xffff0000, v25
	ds_write_b16_d16_hi v32, v21 offset:816
	v_pk_mul_f32 v[20:21], v[36:37], v[20:21] op_sel_hi:[1,0]
	v_ashrrev_i32_e32 v41, 31, v40
	v_cvt_pk_bf16_f32 v20, v20, v21
	ds_write_b16 v32, v20 offset:35632
	ds_write_b16_d16_hi v31, v20 offset:816
	v_lshlrev_b32_e32 v20, 16, v26
	v_pk_mul_f32 v[20:21], v[36:37], v[20:21] op_sel_hi:[1,0]
	ds_write_b16 v32, v22 offset:1088
	v_cvt_pk_bf16_f32 v20, v20, v21
	ds_write_b16 v32, v20 offset:35904
	ds_write_b16_d16_hi v31, v20 offset:1088
	v_and_b32_e32 v20, 0xffff0000, v26
	v_pk_mul_f32 v[20:21], v[36:37], v[20:21] op_sel_hi:[1,0]
	ds_write_b16_d16_hi v32, v22 offset:1360
	v_cvt_pk_bf16_f32 v20, v20, v21
	ds_write_b16 v32, v20 offset:36176
	ds_write_b16_d16_hi v31, v20 offset:1360
	v_lshlrev_b32_e32 v20, 16, v27
	v_pk_mul_f32 v[20:21], v[36:37], v[20:21] op_sel_hi:[1,0]
	ds_write_b16 v32, v23 offset:1632
	v_cvt_pk_bf16_f32 v20, v20, v21
	v_or_b32_e32 v21, 7, v30
	ds_write_b16 v32, v20 offset:36448
	ds_write_b16_d16_hi v31, v20 offset:1632
	v_and_b32_e32 v20, 0xffff0000, v27
	v_mul_lo_u32 v21, v21, s19
	v_add_lshl_u32 v22, v21, v11, 1
	v_pk_mul_f32 v[20:21], v[36:37], v[20:21] op_sel_hi:[1,0]
	v_add_u32_e32 v24, 0, v22
	v_cvt_pk_bf16_f32 v20, v20, v21
	v_add_u32_e32 v21, s3, v22
	ds_write_b16 v24, v20 offset:34816
	ds_write_b16_d16_hi v21, v20
	v_add_u32_e32 v20, 0x400, v39
	v_ashrrev_i32_e32 v22, 4, v20
	v_and_b32_e32 v42, -8, v22
	v_lshlrev_b32_e32 v20, 16, v16
	v_mul_lo_u32 v21, v42, s19
	ds_write_b16_d16_hi v24, v23
	v_add_lshl_u32 v23, v21, v11, 1
	v_pk_mul_f32 v[20:21], v[36:37], v[20:21] op_sel_hi:[1,0]
	v_add_u32_e32 v24, 0, v23
	v_cvt_pk_bf16_f32 v20, v20, v21
	v_add_u32_e32 v23, s3, v23
	v_and_b32_e32 v16, 0xffff0000, v16
	ds_write_b16 v24, v20 offset:34816
	ds_write_b16_d16_hi v23, v20
	v_pk_mul_f32 v[20:21], v[36:37], v[16:17] op_sel_hi:[1,0]
	ds_write_b16 v24, v12
	ds_write_b16_d16_hi v24, v12 offset:272
	v_cvt_pk_bf16_f32 v12, v20, v21
	ds_write_b16 v24, v12 offset:35088
	ds_write_b16_d16_hi v23, v12 offset:272
	v_lshlrev_b32_e32 v12, 16, v17
	v_pk_mul_f32 v[20:21], v[36:37], v[12:13] op_sel_hi:[1,0]
	ds_write_b16 v24, v13 offset:544
	v_cvt_pk_bf16_f32 v12, v20, v21
; DI unsigned pk2(float lo, float hi) { const f32n2 v = {lo, hi}; return __builtin_bit_cast(unsigned, __builtin_convertvector(v, bf16n2)); }
; DI float bflo(unsigned w) { return __uint_as_float(w << 16); }
; DI float bfhi(unsigned w) { return __uint_as_float(w & 0xffff0000u); }
; DI void summary_unit(LAS unsigned char* lds, const Ctx& c, int chunk, int head, int nchunk, int nhead, u32x4 (&v8r)[4], u32x4 (&k8r)[4], int tid, int lane, int wid) {
;     ...
;     for (int i = 0; i < 4; ++i) { const int idx = tid + 512 * i, s = idx & 127, ch = idx >> 7;
;         const u32x4 v8 = v8r[i], k8 = k8r[i]; const float wf = vW[s], wb = vW[128 + s];
; #pragma unroll
;         for (int e = 0; e < 8; ++e) { const unsigned vw = v8[e >> 1], kw = k8[e >> 1]; const float kf = (e & 1) ? bfhi(kw) : bflo(kw);
;             LVT[(8 * ch + e) * 136 + s] = (bf16_t)((e & 1) ? (vw >> 16) : (vw & 0xffffu));
;             const unsigned fb = pk2(wf * kf, wb * kf); LKF[(8 * ch + e) * 136 + s] = (bf16_t)(fb & 0xffffu); LKB[(8 * ch + e) * 136 + s] = (bf16_t)(fb >> 16); } }
;     summary_prefetch(c, nchunk, nhead, tid, v8r, k8r);
;     __syncthreads();
	ds_write_b16 v24, v12 offset:35360
	ds_write_b16_d16_hi v23, v12 offset:544
	v_and_b32_e32 v12, 0xffff0000, v17
	ds_write_b16_d16_hi v24, v13 offset:816
	v_pk_mul_f32 v[12:13], v[36:37], v[12:13] op_sel_hi:[1,0]
	v_ashrrev_i32_e32 v43, 31, v42
	v_cvt_pk_bf16_f32 v12, v12, v13
	ds_write_b16 v24, v12 offset:35632
	ds_write_b16_d16_hi v23, v12 offset:816
	v_lshlrev_b32_e32 v12, 16, v18
	v_pk_mul_f32 v[12:13], v[36:37], v[12:13] op_sel_hi:[1,0]
	ds_write_b16 v24, v14 offset:1088
	v_cvt_pk_bf16_f32 v12, v12, v13
	ds_write_b16 v24, v12 offset:35904
	ds_write_b16_d16_hi v23, v12 offset:1088
	v_and_b32_e32 v12, 0xffff0000, v18
	v_pk_mul_f32 v[12:13], v[36:37], v[12:13] op_sel_hi:[1,0]
	ds_write_b16_d16_hi v24, v14 offset:1360
	v_cvt_pk_bf16_f32 v12, v12, v13
	ds_write_b16 v24, v12 offset:36176
	ds_write_b16_d16_hi v23, v12 offset:1360
	v_lshlrev_b32_e32 v12, 16, v19
	v_pk_mul_f32 v[12:13], v[36:37], v[12:13] op_sel_hi:[1,0]
	ds_write_b16 v24, v15 offset:1632
	v_cvt_pk_bf16_f32 v12, v12, v13
	v_or_b32_e32 v13, 7, v22
	ds_write_b16 v24, v12 offset:36448
	ds_write_b16_d16_hi v23, v12 offset:1632
	v_and_b32_e32 v12, 0xffff0000, v19
	v_mul_lo_u32 v13, v13, s19
	v_add_lshl_u32 v14, v13, v11, 1
	v_pk_mul_f32 v[12:13], v[36:37], v[12:13] op_sel_hi:[1,0]
	v_add_u32_e32 v16, 0, v14
	v_cvt_pk_bf16_f32 v12, v12, v13
	v_add_u32_e32 v13, s3, v14
	ds_write_b16 v16, v12 offset:34816
	ds_write_b16_d16_hi v13, v12
	v_add_u32_e32 v12, 0x600, v39
	v_ashrrev_i32_e32 v14, 4, v12
	v_and_b32_e32 v44, -8, v14
	v_lshlrev_b32_e32 v12, 16, v4
	v_mul_lo_u32 v13, v44, s19
	ds_write_b16_d16_hi v16, v15
	v_add_lshl_u32 v15, v13, v11, 1
	v_pk_mul_f32 v[12:13], v[36:37], v[12:13] op_sel_hi:[1,0]
	v_add_u32_e32 v16, 0, v15
	v_cvt_pk_bf16_f32 v12, v12, v13
	v_add_u32_e32 v15, s3, v15
	v_and_b32_e32 v4, 0xffff0000, v4
	ds_write_b16 v16, v12 offset:34816
	ds_write_b16_d16_hi v15, v12
	v_pk_mul_f32 v[12:13], v[36:37], v[4:5] op_sel_hi:[1,0]
	ds_write_b16 v16, v0
	ds_write_b16_d16_hi v16, v0 offset:272
	v_cvt_pk_bf16_f32 v0, v12, v13
	ds_write_b16 v16, v0 offset:35088
	ds_write_b16_d16_hi v15, v0 offset:272
	v_lshlrev_b32_e32 v0, 16, v5
	v_pk_mul_f32 v[12:13], v[36:37], v[0:1] op_sel_hi:[1,0]
	ds_write_b16 v16, v1 offset:544
	v_cvt_pk_bf16_f32 v0, v12, v13
	ds_write_b16 v16, v0 offset:35360
	ds_write_b16_d16_hi v15, v0 offset:544
	v_and_b32_e32 v0, 0xffff0000, v5
	ds_write_b16_d16_hi v16, v1 offset:816
	v_pk_mul_f32 v[0:1], v[36:37], v[0:1] op_sel_hi:[1,0]
	v_ashrrev_i32_e32 v45, 31, v44
	v_cvt_pk_bf16_f32 v0, v0, v1
	ds_write_b16 v16, v0 offset:35632
	ds_write_b16_d16_hi v15, v0 offset:816
	v_lshlrev_b32_e32 v0, 16, v6
	v_pk_mul_f32 v[0:1], v[36:37], v[0:1] op_sel_hi:[1,0]
	ds_write_b16 v16, v2 offset:1088
	v_cvt_pk_bf16_f32 v0, v0, v1
	ds_write_b16 v16, v0 offset:35904
	ds_write_b16_d16_hi v15, v0 offset:1088
	v_and_b32_e32 v0, 0xffff0000, v6
	v_pk_mul_f32 v[0:1], v[36:37], v[0:1] op_sel_hi:[1,0]
	ds_write_b16_d16_hi v16, v2 offset:1360
	v_cvt_pk_bf16_f32 v0, v0, v1
	ds_write_b16 v16, v0 offset:36176
	ds_write_b16_d16_hi v15, v0 offset:1360
	v_lshlrev_b32_e32 v0, 16, v7
	v_pk_mul_f32 v[0:1], v[36:37], v[0:1] op_sel_hi:[1,0]
	ds_write_b16 v16, v3 offset:1632
	v_cvt_pk_bf16_f32 v0, v0, v1
	v_or_b32_e32 v1, 7, v14
	ds_write_b16 v16, v0 offset:36448
	ds_write_b16_d16_hi v15, v0 offset:1632
	v_and_b32_e32 v0, 0xffff0000, v7
	v_mul_lo_u32 v1, v1, s19
	v_add_lshl_u32 v2, v1, v11, 1
	v_pk_mul_f32 v[0:1], v[36:37], v[0:1] op_sel_hi:[1,0]
	v_add_u32_e32 v4, 0, v2
	v_cvt_pk_bf16_f32 v0, v0, v1
	v_add_u32_e32 v1, s3, v2
	s_lshr_b32 s3, s2, 2
	s_lshl_b32 s3, s3, 7
	v_sub_u32_e32 v196, 0x7f, v38
	v_cndmask_b32_e64 v196, v196, v38, s[0:1]
	v_or_b32_e32 v197, 1, v38
	v_sub_u32_e32 v198, 0x7f, v197
	v_cndmask_b32_e64 v197, v198, v197, s[0:1]
	v_add_u32_e32 v196, s3, v196
	v_add_u32_e32 v197, s3, v197
	s_and_b32 s3, s2, 3
	s_lshl_b32 s3, s3, 2
	v_lshlrev_b32_e32 v196, 6, v196
	v_lshlrev_b32_e32 v197, 6, v197
	v_add_u32_e32 v196, s3, v196
	v_add_u32_e32 v197, s3, v197
	global_load_dword v192, v196, s[46:47]
	global_load_dword v193, v196, s[46:47] offset:32
	global_load_dword v194, v197, s[46:47]
	global_load_dword v195, v197, s[46:47] offset:32
	s_lshl_b32 s3, s2, 5
	ds_write_b16 v4, v0 offset:34816
	ds_write_b16_d16_hi v1, v0
	v_mov_b32_e32 v0, s3
	s_movk_i32 s3, 0x7f
	v_bfi_b32 v0, s3, v39, v0
	v_ashrrev_i32_e32 v1, 31, v0
	s_lshl_b32 s2, s2, 7
	v_lshlrev_b64 v[0:1], 9, v[0:1]
	s_and_b32 s2, s2, 0x180
	v_or_b32_e32 v0, s2, v0
	v_ashrrev_i32_e32 v11, 31, v10
	ds_write_b16_d16_hi v4, v3
	v_lshl_add_u64 v[2:3], v[0:1], 0, v[10:11]
	v_lshlrev_b64 v[2:3], 1, v[2:3]
	v_lshl_add_u64 v[4:5], s[54:55], 0, v[2:3]
	v_lshl_add_u64 v[2:3], s[52:53], 0, v[2:3]
	global_load_dwordx4 v[28:31], v[4:5], off
	global_load_dwordx4 v[32:35], v[2:3], off
	v_lshl_add_u64 v[2:3], v[0:1], 0, v[40:41]
	v_lshlrev_b64 v[2:3], 1, v[2:3]
	v_lshl_add_u64 v[4:5], s[54:55], 0, v[2:3]
	v_lshl_add_u64 v[2:3], s[52:53], 0, v[2:3]
	global_load_dwordx4 v[20:23], v[4:5], off
	global_load_dwordx4 v[24:27], v[2:3], off
	v_lshl_add_u64 v[2:3], v[0:1], 0, v[42:43]
	v_lshlrev_b64 v[2:3], 1, v[2:3]
	v_and_b32_e32 v10, 24, v38
	v_and_b32_e32 v11, 3, v8
	v_lshl_add_u64 v[4:5], s[54:55], 0, v[2:3]
	v_lshl_add_u64 v[2:3], s[52:53], 0, v[2:3]
	v_lshl_add_u64 v[0:1], v[0:1], 0, v[44:45]
	v_or3_b32 v10, v11, v10, s92
	s_movk_i32 s2, 0x110
	global_load_dwordx4 v[12:15], v[4:5], off
	global_load_dwordx4 v[16:19], v[2:3], off
	v_lshlrev_b64 v[4:5], 1, v[0:1]
	v_and_b32_e32 v69, -16, v8
	v_mul_lo_u32 v10, v10, s2
	v_ashrrev_i32_e32 v8, 1, v8
	v_lshl_add_u64 v[0:1], s[54:55], 0, v[4:5]
	v_lshl_add_u64 v[4:5], s[52:53], 0, v[4:5]
	v_add3_u32 v10, s91, v69, v10
	v_and_b32_e32 v8, -8, v8
	global_load_dwordx4 v[0:3], v[0:1], off
	s_add_i32 s2, s13, s93
	global_load_dwordx4 v[4:7], v[4:5], off
	s_waitcnt lgkmcnt(0)
	s_barrier
; #define LAS __attribute__((address_space(3)))
; DI unsigned pk2(float lo, float hi) { const f32n2 v = {lo, hi}; return __builtin_bit_cast(unsigned, __builtin_convertvector(v, bf16n2)); }
; #define MFMA16(a, b, c) __builtin_amdgcn_mfma_f32_16x16x32_bf16((a), (b), (c), 0, 0, 0)
; DI void summary_unit(LAS unsigned char* lds, const Ctx& c, int chunk, int head, int nchunk, int nhead, u32x4 (&v8r)[4], u32x4 (&k8r)[4], int tid, int lane, int wid) {
;     ...
;     const int d = wid & 1, cgp = wid >> 1;
;     LAS const unsigned char* LKD = (LAS const unsigned char*)(d ? LKB : LKF);
;     bf16x8 Y[2][4];
; #pragma unroll
;     for (int ci = 0; ci < 2; ++ci)
; #pragma unroll
;         for (int ks = 0; ks < 4; ++ks) Y[ci][ks] = *(LAS const bf16x8*)(LKD + (32 * cgp + 8 * (fr >> 2) + 4 * ci + (fr & 3)) * 272 + (32 * ks + 8 * fq) * 2);
;     bf16_t* ST = (bf16_t*)(c.out) + ((size_t)(d * NCHUNK + chunk) * 4 + head) * ST_ELEMS;
; #pragma unroll
;     for (int rt = 0; rt < 9; ++rt) {
;         bf16x8 X[4];
; #pragma unroll
;         for (int ks = 0; ks < 4; ++ks) {
;             if (rt < 8) X[ks] = *(LAS const bf16x8*)((LAS const unsigned char*)LVT + (16 * rt + fr) * 272 + (32 * ks + 8 * fq) * 2);
;             else { const short o = fr == 0 ? (short)0x3F80 : (short)0; X[ks] = (bf16x8){o, o, o, o, o, o, o, o}; } }
;         f32x4 a2[2];
; #pragma unroll
;         for (int ci = 0; ci < 2; ++ci) { a2[ci] = (f32x4){0.f, 0.f, 0.f, 0.f};
; #pragma unroll
;             for (int ks = 0; ks < 4; ++ks) a2[ci] = MFMA16(Y[ci][ks], X[ks], a2[ci]); }
;         { const int v = 16 * rt + fr, k = 32 * cgp + 8 * fq;
;           if (rt < 8 || fr == 0) { u32x4 w; w.x = pk2(a2[0][0], a2[0][1]); w.y = pk2(a2[0][2], a2[0][3]); w.z = pk2(a2[1][0], a2[1][1]); w.w = pk2(a2[1][2], a2[1][3]); *(u32x4*)(ST + (size_t)v * 128 + k) = w; } }
	ds_read_b128 v[64:67], v10
	ds_read_b128 v[60:63], v10 offset:64
	ds_read_b128 v[56:59], v10 offset:128
	ds_read_b128 v[52:55], v10 offset:192
	ds_read_b128 v[48:51], v10 offset:1088
	ds_read_b128 v[44:47], v10 offset:1152
	ds_read_b128 v[40:43], v10 offset:1216
	ds_read_b128 v[36:39], v10 offset:1280
	v_add_u32_e32 v10, s92, v8
	v_mul_u32_u24_e32 v8, 0x110, v68
	v_add3_u32 v71, 0, v69, v8
	ds_read_b128 v[72:75], v71
	ds_read_b128 v[76:79], v71 offset:64
	ds_read_b128 v[80:83], v71 offset:128
	ds_read_b128 v[84:87], v71 offset:192
	s_waitcnt lgkmcnt(3)
	v_mfma_f32_16x16x32_bf16 v[88:91], v[64:67], v[72:75], 0
	s_ashr_i32 s3, s2, 31
	s_lshl_b64 s[2:3], s[2:3], 2
	s_add_u32 s2, s12, s2
	v_mfma_f32_16x16x32_bf16 v[72:75], v[48:51], v[72:75], 0
	s_addc_u32 s3, s4, s3
	s_mul_i32 s3, s3, 0x8100
	s_mul_hi_u32 s4, s2, 0x8100
	s_waitcnt lgkmcnt(2)
	v_mfma_f32_16x16x32_bf16 v[88:91], v[60:63], v[76:79], v[88:91]
	v_readlane_b32 s8, v252, 30
	s_add_i32 s3, s4, s3
	s_mul_i32 s2, s2, 0x8100
	v_mfma_f32_16x16x32_bf16 v[72:75], v[44:47], v[76:79], v[72:75]
	v_readlane_b32 s10, v252, 32
	v_readlane_b32 s11, v252, 33
	s_add_u32 s4, s10, s2
	s_waitcnt lgkmcnt(1)
	v_mfma_f32_16x16x32_bf16 v[88:91], v[56:59], v[80:83], v[88:91]
	s_addc_u32 s5, s11, s3
	v_ashrrev_i32_e32 v11, 31, v10
	v_lshl_add_u64 v[10:11], v[10:11], 1, s[4:5]
	v_mfma_f32_16x16x32_bf16 v[72:75], v[40:43], v[80:83], v[72:75]
	v_lshlrev_b32_e32 v8, 8, v68
	v_cmp_eq_u32_e64 s[2:3], 0, v68
	v_lshl_add_u64 v[68:69], v[10:11], 0, v[8:9]
	s_waitcnt lgkmcnt(0)
	v_mfma_f32_16x16x32_bf16 v[88:91], v[52:55], v[84:87], v[88:91]
	s_movk_i32 s4, 0x2000
	v_add_co_u32_e32 v92, vcc, s4, v68
	v_mfma_f32_16x16x32_bf16 v[72:75], v[36:39], v[84:87], v[72:75]
	s_nop 0
	v_addc_co_u32_e32 v93, vcc, 0, v69, vcc
	s_nop 2
	v_cvt_pk_bf16_f32 v76, v88, v89
	v_cvt_pk_bf16_f32 v77, v90, v91
	s_movk_i32 s4, 0x4000
	v_cvt_pk_bf16_f32 v78, v72, v73
	v_cvt_pk_bf16_f32 v79, v74, v75
	global_store_dwordx4 v[68:69], v[76:79], off
	ds_read_b128 v[72:75], v71 offset:4352
	ds_read_b128 v[76:79], v71 offset:4416
	ds_read_b128 v[80:83], v71 offset:4480
	ds_read_b128 v[84:87], v71 offset:4544
	s_waitcnt lgkmcnt(3)
	v_mfma_f32_16x16x32_bf16 v[88:91], v[64:67], v[72:75], 0
	v_cndmask_b32_e64 v70, 0, v158, s[2:3]
	v_readlane_b32 s9, v252, 31
	v_mfma_f32_16x16x32_bf16 v[72:75], v[48:51], v[72:75], 0
	s_waitcnt lgkmcnt(2)
	v_mfma_f32_16x16x32_bf16 v[88:91], v[60:63], v[76:79], v[88:91]
	v_mfma_f32_16x16x32_bf16 v[72:75], v[44:47], v[76:79], v[72:75]
	s_waitcnt lgkmcnt(1)
	v_mfma_f32_16x16x32_bf16 v[88:91], v[56:59], v[80:83], v[88:91]
	v_mfma_f32_16x16x32_bf16 v[72:75], v[40:43], v[80:83], v[72:75]
	s_waitcnt lgkmcnt(0)
	v_mfma_f32_16x16x32_bf16 v[88:91], v[52:55], v[84:87], v[88:91]
	v_mfma_f32_16x16x32_bf16 v[72:75], v[36:39], v[84:87], v[72:75]
	s_nop 6
	v_cvt_pk_bf16_f32 v76, v88, v89
	v_cvt_pk_bf16_f32 v77, v90, v91
	v_cvt_pk_bf16_f32 v78, v72, v73
	v_cvt_pk_bf16_f32 v79, v74, v75
	global_store_dwordx4 v[92:93], v[76:79], off offset:-4096
	ds_read_b128 v[72:75], v71 offset:8704
	ds_read_b128 v[76:79], v71 offset:8768
	ds_read_b128 v[80:83], v71 offset:8832
	ds_read_b128 v[84:87], v71 offset:8896
	s_waitcnt lgkmcnt(3)
	v_mfma_f32_16x16x32_bf16 v[88:91], v[64:67], v[72:75], 0
	v_mfma_f32_16x16x32_bf16 v[72:75], v[48:51], v[72:75], 0
	s_waitcnt lgkmcnt(2)
	v_mfma_f32_16x16x32_bf16 v[88:91], v[60:63], v[76:79], v[88:91]
	v_mfma_f32_16x16x32_bf16 v[72:75], v[44:47], v[76:79], v[72:75]
	s_waitcnt lgkmcnt(1)
	v_mfma_f32_16x16x32_bf16 v[88:91], v[56:59], v[80:83], v[88:91]
	v_mfma_f32_16x16x32_bf16 v[72:75], v[40:43], v[80:83], v[72:75]
	s_waitcnt lgkmcnt(0)
	v_mfma_f32_16x16x32_bf16 v[88:91], v[52:55], v[84:87], v[88:91]
	v_mfma_f32_16x16x32_bf16 v[72:75], v[36:39], v[84:87], v[72:75]
	s_nop 6
	v_cvt_pk_bf16_f32 v76, v88, v89
	v_cvt_pk_bf16_f32 v77, v90, v91
	v_cvt_pk_bf16_f32 v78, v72, v73
	v_cvt_pk_bf16_f32 v79, v74, v75
	global_store_dwordx4 v[92:93], v[76:79], off
	ds_read_b128 v[72:75], v71 offset:13056
	ds_read_b128 v[76:79], v71 offset:13120
	ds_read_b128 v[80:83], v71 offset:13184
	ds_read_b128 v[84:87], v71 offset:13248
	s_waitcnt lgkmcnt(3)
	v_mfma_f32_16x16x32_bf16 v[88:91], v[64:67], v[72:75], 0
	v_add_co_u32_e32 v92, vcc, s4, v68
	s_movk_i32 s4, 0x6000
	v_mfma_f32_16x16x32_bf16 v[72:75], v[48:51], v[72:75], 0
	v_addc_co_u32_e32 v93, vcc, 0, v69, vcc
	s_waitcnt lgkmcnt(2)
	v_mfma_f32_16x16x32_bf16 v[88:91], v[60:63], v[76:79], v[88:91]
	v_mfma_f32_16x16x32_bf16 v[72:75], v[44:47], v[76:79], v[72:75]
	s_waitcnt lgkmcnt(1)
	v_mfma_f32_16x16x32_bf16 v[88:91], v[56:59], v[80:83], v[88:91]
	v_mfma_f32_16x16x32_bf16 v[72:75], v[40:43], v[80:83], v[72:75]
	s_waitcnt lgkmcnt(0)
	v_mfma_f32_16x16x32_bf16 v[88:91], v[52:55], v[84:87], v[88:91]
	v_mfma_f32_16x16x32_bf16 v[72:75], v[36:39], v[84:87], v[72:75]
	s_nop 6
	v_cvt_pk_bf16_f32 v76, v88, v89
	v_cvt_pk_bf16_f32 v77, v90, v91
	v_cvt_pk_bf16_f32 v78, v72, v73
	v_cvt_pk_bf16_f32 v79, v74, v75
	global_store_dwordx4 v[92:93], v[76:79], off offset:-4096
	ds_read_b128 v[72:75], v71 offset:17408
	ds_read_b128 v[76:79], v71 offset:17472
	ds_read_b128 v[80:83], v71 offset:17536
	ds_read_b128 v[84:87], v71 offset:17600
	s_waitcnt lgkmcnt(3)
; #define LAS __attribute__((address_space(3)))
; DI unsigned pk2(float lo, float hi) { const f32n2 v = {lo, hi}; return __builtin_bit_cast(unsigned, __builtin_convertvector(v, bf16n2)); }
; #define MFMA16(a, b, c) __builtin_amdgcn_mfma_f32_16x16x32_bf16((a), (b), (c), 0, 0, 0)
; DI void summary_unit(LAS unsigned char* lds, const Ctx& c, int chunk, int head, int nchunk, int nhead, u32x4 (&v8r)[4], u32x4 (&k8r)[4], int tid, int lane, int wid) {
;     ...
;     for (int rt = 0; rt < 9; ++rt) {
;         bf16x8 X[4];
; #pragma unroll
;         for (int ks = 0; ks < 4; ++ks) {
;             if (rt < 8) X[ks] = *(LAS const bf16x8*)((LAS const unsigned char*)LVT + (16 * rt + fr) * 272 + (32 * ks + 8 * fq) * 2);
;             else { const short o = fr == 0 ? (short)0x3F80 : (short)0; X[ks] = (bf16x8){o, o, o, o, o, o, o, o}; } }
;         f32x4 a2[2];
; #pragma unroll
;         for (int ci = 0; ci < 2; ++ci) { a2[ci] = (f32x4){0.f, 0.f, 0.f, 0.f};
; #pragma unroll
;             for (int ks = 0; ks < 4; ++ks) a2[ci] = MFMA16(Y[ci][ks], X[ks], a2[ci]); }
;         { const int v = 16 * rt + fr, k = 32 * cgp + 8 * fq;
;           if (rt < 8 || fr == 0) { u32x4 w; w.x = pk2(a2[0][0], a2[0][1]); w.y = pk2(a2[0][2], a2[0][3]); w.z = pk2(a2[1][0], a2[1][1]); w.w = pk2(a2[1][2], a2[1][3]); *(u32x4*)(ST + (size_t)v * 128 + k) = w; } }
;     }
;     __syncthreads();
	v_mfma_f32_16x16x32_bf16 v[88:91], v[64:67], v[72:75], 0
	v_mfma_f32_16x16x32_bf16 v[72:75], v[48:51], v[72:75], 0
	s_waitcnt lgkmcnt(2)
	v_mfma_f32_16x16x32_bf16 v[88:91], v[60:63], v[76:79], v[88:91]
	v_mfma_f32_16x16x32_bf16 v[72:75], v[44:47], v[76:79], v[72:75]
	s_waitcnt lgkmcnt(1)
	v_mfma_f32_16x16x32_bf16 v[88:91], v[56:59], v[80:83], v[88:91]
	v_mfma_f32_16x16x32_bf16 v[72:75], v[40:43], v[80:83], v[72:75]
	s_waitcnt lgkmcnt(0)
	v_mfma_f32_16x16x32_bf16 v[88:91], v[52:55], v[84:87], v[88:91]
	v_mfma_f32_16x16x32_bf16 v[72:75], v[36:39], v[84:87], v[72:75]
	s_nop 6
	v_cvt_pk_bf16_f32 v76, v88, v89
	v_cvt_pk_bf16_f32 v77, v90, v91
	v_cvt_pk_bf16_f32 v78, v72, v73
	v_cvt_pk_bf16_f32 v79, v74, v75
	global_store_dwordx4 v[92:93], v[76:79], off
	ds_read_b128 v[72:75], v71 offset:21760
	ds_read_b128 v[76:79], v71 offset:21824
	ds_read_b128 v[80:83], v71 offset:21888
	ds_read_b128 v[84:87], v71 offset:21952
	s_waitcnt lgkmcnt(3)
	v_mfma_f32_16x16x32_bf16 v[88:91], v[64:67], v[72:75], 0
	v_add_co_u32_e32 v92, vcc, s4, v68
	s_movk_i32 s4, 0x7000
	v_mfma_f32_16x16x32_bf16 v[72:75], v[48:51], v[72:75], 0
	v_addc_co_u32_e32 v93, vcc, 0, v69, vcc
	v_add_co_u32_e32 v68, vcc, s4, v68
	s_waitcnt lgkmcnt(2)
	v_mfma_f32_16x16x32_bf16 v[88:91], v[60:63], v[76:79], v[88:91]
	v_addc_co_u32_e32 v69, vcc, 0, v69, vcc
	s_mov_b32 s4, 0x5040100
	v_mfma_f32_16x16x32_bf16 v[72:75], v[44:47], v[76:79], v[72:75]
	s_waitcnt lgkmcnt(1)
	v_mfma_f32_16x16x32_bf16 v[88:91], v[56:59], v[80:83], v[88:91]
	v_mfma_f32_16x16x32_bf16 v[72:75], v[40:43], v[80:83], v[72:75]
	s_waitcnt lgkmcnt(0)
	v_mfma_f32_16x16x32_bf16 v[88:91], v[52:55], v[84:87], v[88:91]
	v_mfma_f32_16x16x32_bf16 v[72:75], v[36:39], v[84:87], v[72:75]
	s_nop 6
	v_cvt_pk_bf16_f32 v76, v88, v89
	v_cvt_pk_bf16_f32 v77, v90, v91
	v_cvt_pk_bf16_f32 v78, v72, v73
	v_cvt_pk_bf16_f32 v79, v74, v75
	global_store_dwordx4 v[92:93], v[76:79], off offset:-4096
	ds_read_b128 v[72:75], v71 offset:26112
	ds_read_b128 v[76:79], v71 offset:26176
	ds_read_b128 v[80:83], v71 offset:26240
	ds_read_b128 v[84:87], v71 offset:26304
	s_waitcnt lgkmcnt(3)
	v_mfma_f32_16x16x32_bf16 v[88:91], v[64:67], v[72:75], 0
	v_mfma_f32_16x16x32_bf16 v[72:75], v[48:51], v[72:75], 0
	s_waitcnt lgkmcnt(2)
	v_mfma_f32_16x16x32_bf16 v[88:91], v[60:63], v[76:79], v[88:91]
	v_mfma_f32_16x16x32_bf16 v[72:75], v[44:47], v[76:79], v[72:75]
	s_waitcnt lgkmcnt(1)
	v_mfma_f32_16x16x32_bf16 v[88:91], v[56:59], v[80:83], v[88:91]
	v_mfma_f32_16x16x32_bf16 v[72:75], v[40:43], v[80:83], v[72:75]
	s_waitcnt lgkmcnt(0)
	v_mfma_f32_16x16x32_bf16 v[88:91], v[52:55], v[84:87], v[88:91]
	v_mfma_f32_16x16x32_bf16 v[72:75], v[36:39], v[84:87], v[72:75]
	s_nop 6
	v_cvt_pk_bf16_f32 v76, v88, v89
	v_cvt_pk_bf16_f32 v77, v90, v91
	v_cvt_pk_bf16_f32 v78, v72, v73
	v_cvt_pk_bf16_f32 v79, v74, v75
	global_store_dwordx4 v[92:93], v[76:79], off
	ds_read_b128 v[72:75], v71 offset:30464
	ds_read_b128 v[76:79], v71 offset:30528
	ds_read_b128 v[80:83], v71 offset:30592
	ds_read_b128 v[84:87], v71 offset:30656
	s_waitcnt lgkmcnt(3)
	v_mfma_f32_16x16x32_bf16 v[88:91], v[64:67], v[72:75], 0
	v_mfma_f32_16x16x32_bf16 v[72:75], v[48:51], v[72:75], 0
	s_waitcnt lgkmcnt(2)
	v_mfma_f32_16x16x32_bf16 v[88:91], v[60:63], v[76:79], v[88:91]
	v_mfma_f32_16x16x32_bf16 v[72:75], v[44:47], v[76:79], v[72:75]
	s_waitcnt lgkmcnt(1)
	v_mfma_f32_16x16x32_bf16 v[88:91], v[56:59], v[80:83], v[88:91]
	v_mfma_f32_16x16x32_bf16 v[72:75], v[40:43], v[80:83], v[72:75]
	s_waitcnt lgkmcnt(0)
	v_mfma_f32_16x16x32_bf16 v[88:91], v[52:55], v[84:87], v[88:91]
	v_mfma_f32_16x16x32_bf16 v[72:75], v[36:39], v[84:87], v[72:75]
	s_nop 6
	v_cvt_pk_bf16_f32 v76, v88, v89
	v_cvt_pk_bf16_f32 v77, v90, v91
	v_cvt_pk_bf16_f32 v78, v72, v73
	v_cvt_pk_bf16_f32 v79, v74, v75
	global_store_dwordx4 v[68:69], v[76:79], off
	v_perm_b32 v68, v70, v70, s4
	v_mov_b32_e32 v69, v68
	v_mov_b32_e32 v70, v68
	v_mov_b32_e32 v71, v68
	s_nop 1
	v_mfma_f32_16x16x32_bf16 v[64:67], v[64:67], v[68:71], 0
	v_mfma_f32_16x16x32_bf16 v[48:51], v[48:51], v[68:71], 0
	v_mfma_f32_16x16x32_bf16 v[60:63], v[60:63], v[68:71], v[64:67]
	v_mfma_f32_16x16x32_bf16 v[44:47], v[44:47], v[68:71], v[48:51]
	v_mfma_f32_16x16x32_bf16 v[56:59], v[56:59], v[68:71], v[60:63]
	v_mfma_f32_16x16x32_bf16 v[40:43], v[40:43], v[68:71], v[44:47]
	v_mfma_f32_16x16x32_bf16 v[52:55], v[52:55], v[68:71], v[56:59]
	v_mfma_f32_16x16x32_bf16 v[36:39], v[36:39], v[68:71], v[40:43]
	s_and_saveexec_b64 s[4:5], s[2:3]
	s_cbranch_execz .LBB0_204
	v_add_co_u32_e32 v10, vcc, 0x8000, v10
	s_nop 3
	v_cvt_pk_bf16_f32 v40, v52, v53
	v_cvt_pk_bf16_f32 v41, v54, v55
	v_cvt_pk_bf16_f32 v42, v36, v37
	v_cvt_pk_bf16_f32 v43, v38, v39
	v_addc_co_u32_e32 v11, vcc, 0, v11, vcc
	global_store_dwordx4 v[10:11], v[40:43], off
	s_branch .LBB0_204
